# v72 + SSD state scan (P4): all 32 chunk-state/decay loads of a thread issued in two batches ahead of the recurrence instead of two chunks per round trip
# speedup vs baseline: 1.0084x; 1.0003x over previous
; __device__ __forceinline__ unsigned pk2(float lo, float hi) { f32x2_t v = {lo, hi}; bf16x2_t b = __builtin_convertvector(v, bf16x2_t); return __builtin_bit_cast(unsigned, b); }
; __device__ __forceinline__ float bflo(unsigned u) { return __uint_as_float(u << 16); }
; __device__ __forceinline__ float bfhi(unsigned u) { return __uint_as_float(u & 0xffff0000u); }
; __device__ __forceinline__ void phase4_scan(const Params& p, int bid, int G) {
;     const bfu* states = (const bfu*)(p.ws + WS_STATES);
;     const float* decay = (const float*)(p.ws + WS_DECAY);
;     bfu* hprev = (bfu*)(p.ws + WS_HPREV);
;     for (int i = bid * 512 + threadIdx.x; i < 131072; i += G * 512) {
;         const int e = i * 4, n = e & 127, pp = (e >> 7) & 63, h = (e >> 13) & 15, b = e >> 17;
;         float4 hc = make_float4(0.f, 0.f, 0.f, 0.f);
; #pragma unroll 16
;         for (int c = 0; c < 32; ++c) {
;             const float dec = decay[(b * 32 + c) * 16 + h];
;             const size_t off = ((size_t)((b * 32 + c) * 16 + h) * 64 + pp) * 128 + n;
;             const uint2 su = *(const uint2*)(states + off);
;             const float4 st = make_float4(bflo(su.x), bfhi(su.x), bflo(su.y), bfhi(su.y));
;             uint2 o; o.x = pk2(hc.x, hc.y); o.y = pk2(hc.z, hc.w);
;             *(uint2*)(hprev + off) = o;
;             hc.x = hc.x * dec + st.x; hc.y = hc.y * dec + st.y; hc.z = hc.z * dec + st.z; hc.w = hc.w * dec + st.w;
;         }
;         *(float4*)(p.out + O_SP + ((size_t)(b * 16 + h) * 64 + pp) * 128 + n) = hc;
.LBB0_467:
	v_ashrrev_i32_e32 v81, 15, v178
	v_bfe_u32 v6, v178, 11, 4
	v_lshlrev_b32_e32 v104, 2, v178
	v_and_b32_e32 v104, 0x1ffff, v104
	v_lshlrev_b32_e32 v104, 1, v104
	v_lshl_or_b32 v104, v81, 23, v104
	v_lshlrev_b32_e32 v105, 2, v6
	v_lshl_or_b32 v105, v81, 11, v105
	s_add_u32 s12, s10, 0x22a00000
	s_addc_u32 s13, s11, 0
	s_add_u32 s14, s10, 0x1ca00000
	s_addc_u32 s15, s11, 0
	s_add_u32 s16, s10, 0x20a00000
	s_addc_u32 s17, s11, 0
	v_mov_b32_e32 v115, 0
	v_mov_b32_e32 v114, v104
	v_mov_b32_e32 v117, 0
	v_mov_b32_e32 v116, v104
	v_mov_b32_e32 v119, 0
	v_mov_b32_e32 v118, v105
	v_lshl_add_u64 v[114:115], s[14:15], 0, v[114:115]
	v_lshl_add_u64 v[116:117], s[16:17], 0, v[116:117]
	v_lshl_add_u64 v[118:119], s[12:13], 0, v[118:119]
	s_mov_b64 s[12:13], 0x40000
	global_load_dword v72, v[118:119], off
	global_load_dwordx2 v[8:9], v[114:115], off
	v_lshl_add_u64 v[114:115], v[114:115], 0, s[12:13]
	global_load_dword v73, v[118:119], off offset:64
	global_load_dwordx2 v[10:11], v[114:115], off
	v_lshl_add_u64 v[114:115], v[114:115], 0, s[12:13]
	global_load_dword v74, v[118:119], off offset:128
	global_load_dwordx2 v[12:13], v[114:115], off
	v_lshl_add_u64 v[114:115], v[114:115], 0, s[12:13]
	global_load_dword v75, v[118:119], off offset:192
	global_load_dwordx2 v[14:15], v[114:115], off
	v_lshl_add_u64 v[114:115], v[114:115], 0, s[12:13]
	global_load_dword v76, v[118:119], off offset:256
	global_load_dwordx2 v[16:17], v[114:115], off
	v_lshl_add_u64 v[114:115], v[114:115], 0, s[12:13]
	global_load_dword v77, v[118:119], off offset:320
	global_load_dwordx2 v[18:19], v[114:115], off
	v_lshl_add_u64 v[114:115], v[114:115], 0, s[12:13]
	global_load_dword v78, v[118:119], off offset:384
	global_load_dwordx2 v[20:21], v[114:115], off
	v_lshl_add_u64 v[114:115], v[114:115], 0, s[12:13]
	global_load_dword v79, v[118:119], off offset:448
	global_load_dwordx2 v[22:23], v[114:115], off
	v_lshl_add_u64 v[114:115], v[114:115], 0, s[12:13]
	global_load_dword v80, v[118:119], off offset:512
	global_load_dwordx2 v[24:25], v[114:115], off
	v_lshl_add_u64 v[114:115], v[114:115], 0, s[12:13]
	global_load_dword v81, v[118:119], off offset:576
	global_load_dwordx2 v[26:27], v[114:115], off
	v_lshl_add_u64 v[114:115], v[114:115], 0, s[12:13]
	global_load_dword v82, v[118:119], off offset:640
	global_load_dwordx2 v[28:29], v[114:115], off
	v_lshl_add_u64 v[114:115], v[114:115], 0, s[12:13]
	global_load_dword v83, v[118:119], off offset:704
	global_load_dwordx2 v[30:31], v[114:115], off
	v_lshl_add_u64 v[114:115], v[114:115], 0, s[12:13]
	global_load_dword v84, v[118:119], off offset:768
	global_load_dwordx2 v[32:33], v[114:115], off
	v_lshl_add_u64 v[114:115], v[114:115], 0, s[12:13]
	global_load_dword v85, v[118:119], off offset:832
	global_load_dwordx2 v[34:35], v[114:115], off
	v_lshl_add_u64 v[114:115], v[114:115], 0, s[12:13]
	global_load_dword v86, v[118:119], off offset:896
	global_load_dwordx2 v[36:37], v[114:115], off
	v_lshl_add_u64 v[114:115], v[114:115], 0, s[12:13]
	global_load_dword v87, v[118:119], off offset:960
	global_load_dwordx2 v[38:39], v[114:115], off
	v_lshl_add_u64 v[114:115], v[114:115], 0, s[12:13]
	v_mov_b32_e32 v0, 0
	v_mov_b32_e32 v1, 0
	v_mov_b32_e32 v2, 0
	v_mov_b32_e32 v3, 0
	v_cvt_pk_bf16_f32 v106, v0, v1
	v_cvt_pk_bf16_f32 v107, v2, v3
	global_store_dwordx2 v[116:117], v[106:107], off
	v_lshl_add_u64 v[116:117], v[116:117], 0, s[12:13]
	s_waitcnt vmcnt(31)
	v_lshlrev_b32_e32 v110, 16, v8
	v_and_b32_e32 v111, 0xffff0000, v8
	v_lshlrev_b32_e32 v112, 16, v9
	v_and_b32_e32 v113, 0xffff0000, v9
	v_fma_f32 v0, v0, v72, v110
	v_fma_f32 v1, v1, v72, v111
	v_fma_f32 v2, v2, v72, v112
	v_fma_f32 v3, v3, v72, v113
	global_load_dword v88, v[118:119], off offset:1024
	global_load_dwordx2 v[40:41], v[114:115], off
	v_lshl_add_u64 v[114:115], v[114:115], 0, s[12:13]
	v_cvt_pk_bf16_f32 v108, v0, v1
	v_cvt_pk_bf16_f32 v109, v2, v3
	global_store_dwordx2 v[116:117], v[108:109], off
	v_lshl_add_u64 v[116:117], v[116:117], 0, s[12:13]
	s_waitcnt vmcnt(32)
	v_lshlrev_b32_e32 v110, 16, v10
	v_and_b32_e32 v111, 0xffff0000, v10
	v_lshlrev_b32_e32 v112, 16, v11
	v_and_b32_e32 v113, 0xffff0000, v11
	v_fma_f32 v0, v0, v73, v110
	v_fma_f32 v1, v1, v73, v111
	v_fma_f32 v2, v2, v73, v112
	v_fma_f32 v3, v3, v73, v113
	global_load_dword v89, v[118:119], off offset:1088
	global_load_dwordx2 v[42:43], v[114:115], off
	v_lshl_add_u64 v[114:115], v[114:115], 0, s[12:13]
	v_cvt_pk_bf16_f32 v106, v0, v1
	v_cvt_pk_bf16_f32 v107, v2, v3
	global_store_dwordx2 v[116:117], v[106:107], off
	v_lshl_add_u64 v[116:117], v[116:117], 0, s[12:13]
	s_waitcnt vmcnt(33)
	v_lshlrev_b32_e32 v110, 16, v12
	v_and_b32_e32 v111, 0xffff0000, v12
	v_lshlrev_b32_e32 v112, 16, v13
	v_and_b32_e32 v113, 0xffff0000, v13
	v_fma_f32 v0, v0, v74, v110
	v_fma_f32 v1, v1, v74, v111
	v_fma_f32 v2, v2, v74, v112
	v_fma_f32 v3, v3, v74, v113
	global_load_dword v90, v[118:119], off offset:1152
	global_load_dwordx2 v[44:45], v[114:115], off
	v_lshl_add_u64 v[114:115], v[114:115], 0, s[12:13]
	v_cvt_pk_bf16_f32 v108, v0, v1
	v_cvt_pk_bf16_f32 v109, v2, v3
	global_store_dwordx2 v[116:117], v[108:109], off
	v_lshl_add_u64 v[116:117], v[116:117], 0, s[12:13]
	s_waitcnt vmcnt(34)
	v_lshlrev_b32_e32 v110, 16, v14
	v_and_b32_e32 v111, 0xffff0000, v14
	v_lshlrev_b32_e32 v112, 16, v15
	v_and_b32_e32 v113, 0xffff0000, v15
	v_fma_f32 v0, v0, v75, v110
	v_fma_f32 v1, v1, v75, v111
	v_fma_f32 v2, v2, v75, v112
	v_fma_f32 v3, v3, v75, v113
	global_load_dword v91, v[118:119], off offset:1216
	global_load_dwordx2 v[46:47], v[114:115], off
	v_lshl_add_u64 v[114:115], v[114:115], 0, s[12:13]
	v_cvt_pk_bf16_f32 v106, v0, v1
	v_cvt_pk_bf16_f32 v107, v2, v3
	global_store_dwordx2 v[116:117], v[106:107], off
	v_lshl_add_u64 v[116:117], v[116:117], 0, s[12:13]
	s_waitcnt vmcnt(35)
; __device__ __forceinline__ unsigned pk2(float lo, float hi) { f32x2_t v = {lo, hi}; bf16x2_t b = __builtin_convertvector(v, bf16x2_t); return __builtin_bit_cast(unsigned, b); }
; __device__ __forceinline__ float bflo(unsigned u) { return __uint_as_float(u << 16); }
; __device__ __forceinline__ float bfhi(unsigned u) { return __uint_as_float(u & 0xffff0000u); }
; __device__ __forceinline__ void phase4_scan(const Params& p, int bid, int G) {
;     ...
; #pragma unroll 16
;         for (int c = 0; c < 32; ++c) {
;             const float dec = decay[(b * 32 + c) * 16 + h];
;             const size_t off = ((size_t)((b * 32 + c) * 16 + h) * 64 + pp) * 128 + n;
;             const uint2 su = *(const uint2*)(states + off);
;             const float4 st = make_float4(bflo(su.x), bfhi(su.x), bflo(su.y), bfhi(su.y));
;             uint2 o; o.x = pk2(hc.x, hc.y); o.y = pk2(hc.z, hc.w);
;             *(uint2*)(hprev + off) = o;
;             hc.x = hc.x * dec + st.x; hc.y = hc.y * dec + st.y; hc.z = hc.z * dec + st.z; hc.w = hc.w * dec + st.w;
;         }
	v_lshlrev_b32_e32 v110, 16, v16
	v_and_b32_e32 v111, 0xffff0000, v16
	v_lshlrev_b32_e32 v112, 16, v17
	v_and_b32_e32 v113, 0xffff0000, v17
	v_fma_f32 v0, v0, v76, v110
	v_fma_f32 v1, v1, v76, v111
	v_fma_f32 v2, v2, v76, v112
	v_fma_f32 v3, v3, v76, v113
	global_load_dword v92, v[118:119], off offset:1280
	global_load_dwordx2 v[48:49], v[114:115], off
	v_lshl_add_u64 v[114:115], v[114:115], 0, s[12:13]
	v_cvt_pk_bf16_f32 v108, v0, v1
	v_cvt_pk_bf16_f32 v109, v2, v3
	global_store_dwordx2 v[116:117], v[108:109], off
	v_lshl_add_u64 v[116:117], v[116:117], 0, s[12:13]
	s_waitcnt vmcnt(36)
	v_lshlrev_b32_e32 v110, 16, v18
	v_and_b32_e32 v111, 0xffff0000, v18
	v_lshlrev_b32_e32 v112, 16, v19
	v_and_b32_e32 v113, 0xffff0000, v19
	v_fma_f32 v0, v0, v77, v110
	v_fma_f32 v1, v1, v77, v111
	v_fma_f32 v2, v2, v77, v112
	v_fma_f32 v3, v3, v77, v113
	global_load_dword v93, v[118:119], off offset:1344
	global_load_dwordx2 v[50:51], v[114:115], off
	v_lshl_add_u64 v[114:115], v[114:115], 0, s[12:13]
	v_cvt_pk_bf16_f32 v106, v0, v1
	v_cvt_pk_bf16_f32 v107, v2, v3
	global_store_dwordx2 v[116:117], v[106:107], off
	v_lshl_add_u64 v[116:117], v[116:117], 0, s[12:13]
	s_waitcnt vmcnt(37)
	v_lshlrev_b32_e32 v110, 16, v20
	v_and_b32_e32 v111, 0xffff0000, v20
	v_lshlrev_b32_e32 v112, 16, v21
	v_and_b32_e32 v113, 0xffff0000, v21
	v_fma_f32 v0, v0, v78, v110
	v_fma_f32 v1, v1, v78, v111
	v_fma_f32 v2, v2, v78, v112
	v_fma_f32 v3, v3, v78, v113
	global_load_dword v94, v[118:119], off offset:1408
	global_load_dwordx2 v[52:53], v[114:115], off
	v_lshl_add_u64 v[114:115], v[114:115], 0, s[12:13]
	v_cvt_pk_bf16_f32 v108, v0, v1
	v_cvt_pk_bf16_f32 v109, v2, v3
	global_store_dwordx2 v[116:117], v[108:109], off
	v_lshl_add_u64 v[116:117], v[116:117], 0, s[12:13]
	s_waitcnt vmcnt(38)
	v_lshlrev_b32_e32 v110, 16, v22
	v_and_b32_e32 v111, 0xffff0000, v22
	v_lshlrev_b32_e32 v112, 16, v23
	v_and_b32_e32 v113, 0xffff0000, v23
	v_fma_f32 v0, v0, v79, v110
	v_fma_f32 v1, v1, v79, v111
	v_fma_f32 v2, v2, v79, v112
	v_fma_f32 v3, v3, v79, v113
	global_load_dword v95, v[118:119], off offset:1472
	global_load_dwordx2 v[54:55], v[114:115], off
	v_lshl_add_u64 v[114:115], v[114:115], 0, s[12:13]
	v_cvt_pk_bf16_f32 v106, v0, v1
	v_cvt_pk_bf16_f32 v107, v2, v3
	global_store_dwordx2 v[116:117], v[106:107], off
	v_lshl_add_u64 v[116:117], v[116:117], 0, s[12:13]
	s_waitcnt vmcnt(39)
	v_lshlrev_b32_e32 v110, 16, v24
	v_and_b32_e32 v111, 0xffff0000, v24
	v_lshlrev_b32_e32 v112, 16, v25
	v_and_b32_e32 v113, 0xffff0000, v25
	v_fma_f32 v0, v0, v80, v110
	v_fma_f32 v1, v1, v80, v111
	v_fma_f32 v2, v2, v80, v112
	v_fma_f32 v3, v3, v80, v113
	global_load_dword v96, v[118:119], off offset:1536
	global_load_dwordx2 v[56:57], v[114:115], off
	v_lshl_add_u64 v[114:115], v[114:115], 0, s[12:13]
	v_cvt_pk_bf16_f32 v108, v0, v1
	v_cvt_pk_bf16_f32 v109, v2, v3
	global_store_dwordx2 v[116:117], v[108:109], off
	v_lshl_add_u64 v[116:117], v[116:117], 0, s[12:13]
	s_waitcnt vmcnt(40)
	v_lshlrev_b32_e32 v110, 16, v26
	v_and_b32_e32 v111, 0xffff0000, v26
	v_lshlrev_b32_e32 v112, 16, v27
	v_and_b32_e32 v113, 0xffff0000, v27
	v_fma_f32 v0, v0, v81, v110
	v_fma_f32 v1, v1, v81, v111
	v_fma_f32 v2, v2, v81, v112
	v_fma_f32 v3, v3, v81, v113
	global_load_dword v97, v[118:119], off offset:1600
	global_load_dwordx2 v[58:59], v[114:115], off
	v_lshl_add_u64 v[114:115], v[114:115], 0, s[12:13]
	v_cvt_pk_bf16_f32 v106, v0, v1
	v_cvt_pk_bf16_f32 v107, v2, v3
	global_store_dwordx2 v[116:117], v[106:107], off
	v_lshl_add_u64 v[116:117], v[116:117], 0, s[12:13]
	s_waitcnt vmcnt(41)
	v_lshlrev_b32_e32 v110, 16, v28
	v_and_b32_e32 v111, 0xffff0000, v28
	v_lshlrev_b32_e32 v112, 16, v29
	v_and_b32_e32 v113, 0xffff0000, v29
	v_fma_f32 v0, v0, v82, v110
	v_fma_f32 v1, v1, v82, v111
	v_fma_f32 v2, v2, v82, v112
	v_fma_f32 v3, v3, v82, v113
	global_load_dword v98, v[118:119], off offset:1664
	global_load_dwordx2 v[60:61], v[114:115], off
	v_lshl_add_u64 v[114:115], v[114:115], 0, s[12:13]
	v_cvt_pk_bf16_f32 v108, v0, v1
	v_cvt_pk_bf16_f32 v109, v2, v3
	global_store_dwordx2 v[116:117], v[108:109], off
	v_lshl_add_u64 v[116:117], v[116:117], 0, s[12:13]
	s_waitcnt vmcnt(42)
	v_lshlrev_b32_e32 v110, 16, v30
	v_and_b32_e32 v111, 0xffff0000, v30
	v_lshlrev_b32_e32 v112, 16, v31
	v_and_b32_e32 v113, 0xffff0000, v31
	v_fma_f32 v0, v0, v83, v110
	v_fma_f32 v1, v1, v83, v111
	v_fma_f32 v2, v2, v83, v112
	v_fma_f32 v3, v3, v83, v113
	global_load_dword v99, v[118:119], off offset:1728
	global_load_dwordx2 v[62:63], v[114:115], off
	v_lshl_add_u64 v[114:115], v[114:115], 0, s[12:13]
	v_cvt_pk_bf16_f32 v106, v0, v1
	v_cvt_pk_bf16_f32 v107, v2, v3
	global_store_dwordx2 v[116:117], v[106:107], off
	v_lshl_add_u64 v[116:117], v[116:117], 0, s[12:13]
	s_waitcnt vmcnt(43)
	v_lshlrev_b32_e32 v110, 16, v32
	v_and_b32_e32 v111, 0xffff0000, v32
	v_lshlrev_b32_e32 v112, 16, v33
	v_and_b32_e32 v113, 0xffff0000, v33
	v_fma_f32 v0, v0, v84, v110
	v_fma_f32 v1, v1, v84, v111
	v_fma_f32 v2, v2, v84, v112
	v_fma_f32 v3, v3, v84, v113
	global_load_dword v100, v[118:119], off offset:1792
	global_load_dwordx2 v[64:65], v[114:115], off
	v_lshl_add_u64 v[114:115], v[114:115], 0, s[12:13]
	v_cvt_pk_bf16_f32 v108, v0, v1
	v_cvt_pk_bf16_f32 v109, v2, v3
	global_store_dwordx2 v[116:117], v[108:109], off
	v_lshl_add_u64 v[116:117], v[116:117], 0, s[12:13]
	s_waitcnt vmcnt(44)
; __device__ __forceinline__ unsigned pk2(float lo, float hi) { f32x2_t v = {lo, hi}; bf16x2_t b = __builtin_convertvector(v, bf16x2_t); return __builtin_bit_cast(unsigned, b); }
; __device__ __forceinline__ float bflo(unsigned u) { return __uint_as_float(u << 16); }
; __device__ __forceinline__ float bfhi(unsigned u) { return __uint_as_float(u & 0xffff0000u); }
; __device__ __forceinline__ void phase4_scan(const Params& p, int bid, int G) {
;     ...
; #pragma unroll 16
;         for (int c = 0; c < 32; ++c) {
;             const float dec = decay[(b * 32 + c) * 16 + h];
;             const size_t off = ((size_t)((b * 32 + c) * 16 + h) * 64 + pp) * 128 + n;
;             const uint2 su = *(const uint2*)(states + off);
;             const float4 st = make_float4(bflo(su.x), bfhi(su.x), bflo(su.y), bfhi(su.y));
;             uint2 o; o.x = pk2(hc.x, hc.y); o.y = pk2(hc.z, hc.w);
;             *(uint2*)(hprev + off) = o;
;             hc.x = hc.x * dec + st.x; hc.y = hc.y * dec + st.y; hc.z = hc.z * dec + st.z; hc.w = hc.w * dec + st.w;
;         }
	v_lshlrev_b32_e32 v110, 16, v34
	v_and_b32_e32 v111, 0xffff0000, v34
	v_lshlrev_b32_e32 v112, 16, v35
	v_and_b32_e32 v113, 0xffff0000, v35
	v_fma_f32 v0, v0, v85, v110
	v_fma_f32 v1, v1, v85, v111
	v_fma_f32 v2, v2, v85, v112
	v_fma_f32 v3, v3, v85, v113
	global_load_dword v101, v[118:119], off offset:1856
	global_load_dwordx2 v[66:67], v[114:115], off
	v_lshl_add_u64 v[114:115], v[114:115], 0, s[12:13]
	v_cvt_pk_bf16_f32 v106, v0, v1
	v_cvt_pk_bf16_f32 v107, v2, v3
	global_store_dwordx2 v[116:117], v[106:107], off
	v_lshl_add_u64 v[116:117], v[116:117], 0, s[12:13]
	s_waitcnt vmcnt(45)
	v_lshlrev_b32_e32 v110, 16, v36
	v_and_b32_e32 v111, 0xffff0000, v36
	v_lshlrev_b32_e32 v112, 16, v37
	v_and_b32_e32 v113, 0xffff0000, v37
	v_fma_f32 v0, v0, v86, v110
	v_fma_f32 v1, v1, v86, v111
	v_fma_f32 v2, v2, v86, v112
	v_fma_f32 v3, v3, v86, v113
	global_load_dword v102, v[118:119], off offset:1920
	global_load_dwordx2 v[68:69], v[114:115], off
	v_lshl_add_u64 v[114:115], v[114:115], 0, s[12:13]
	v_cvt_pk_bf16_f32 v108, v0, v1
	v_cvt_pk_bf16_f32 v109, v2, v3
	global_store_dwordx2 v[116:117], v[108:109], off
	v_lshl_add_u64 v[116:117], v[116:117], 0, s[12:13]
	s_waitcnt vmcnt(46)
	v_lshlrev_b32_e32 v110, 16, v38
	v_and_b32_e32 v111, 0xffff0000, v38
	v_lshlrev_b32_e32 v112, 16, v39
	v_and_b32_e32 v113, 0xffff0000, v39
	v_fma_f32 v0, v0, v87, v110
	v_fma_f32 v1, v1, v87, v111
	v_fma_f32 v2, v2, v87, v112
	v_fma_f32 v3, v3, v87, v113
	global_load_dword v103, v[118:119], off offset:1984
	global_load_dwordx2 v[70:71], v[114:115], off
	v_cvt_pk_bf16_f32 v106, v0, v1
	v_cvt_pk_bf16_f32 v107, v2, v3
	global_store_dwordx2 v[116:117], v[106:107], off
	v_lshl_add_u64 v[116:117], v[116:117], 0, s[12:13]
	s_waitcnt vmcnt(46)
	v_lshlrev_b32_e32 v110, 16, v40
	v_and_b32_e32 v111, 0xffff0000, v40
	v_lshlrev_b32_e32 v112, 16, v41
	v_and_b32_e32 v113, 0xffff0000, v41
	v_fma_f32 v0, v0, v88, v110
	v_fma_f32 v1, v1, v88, v111
	v_fma_f32 v2, v2, v88, v112
	v_fma_f32 v3, v3, v88, v113
	v_cvt_pk_bf16_f32 v108, v0, v1
	v_cvt_pk_bf16_f32 v109, v2, v3
	global_store_dwordx2 v[116:117], v[108:109], off
	v_lshl_add_u64 v[116:117], v[116:117], 0, s[12:13]
	s_waitcnt vmcnt(44)
	v_lshlrev_b32_e32 v110, 16, v42
	v_and_b32_e32 v111, 0xffff0000, v42
	v_lshlrev_b32_e32 v112, 16, v43
	v_and_b32_e32 v113, 0xffff0000, v43
	v_fma_f32 v0, v0, v89, v110
	v_fma_f32 v1, v1, v89, v111
	v_fma_f32 v2, v2, v89, v112
	v_fma_f32 v3, v3, v89, v113
	v_cvt_pk_bf16_f32 v106, v0, v1
	v_cvt_pk_bf16_f32 v107, v2, v3
	global_store_dwordx2 v[116:117], v[106:107], off
	v_lshl_add_u64 v[116:117], v[116:117], 0, s[12:13]
	s_waitcnt vmcnt(42)
	v_lshlrev_b32_e32 v110, 16, v44
	v_and_b32_e32 v111, 0xffff0000, v44
	v_lshlrev_b32_e32 v112, 16, v45
	v_and_b32_e32 v113, 0xffff0000, v45
	v_fma_f32 v0, v0, v90, v110
	v_fma_f32 v1, v1, v90, v111
	v_fma_f32 v2, v2, v90, v112
	v_fma_f32 v3, v3, v90, v113
	v_cvt_pk_bf16_f32 v108, v0, v1
	v_cvt_pk_bf16_f32 v109, v2, v3
	global_store_dwordx2 v[116:117], v[108:109], off
	v_lshl_add_u64 v[116:117], v[116:117], 0, s[12:13]
	s_waitcnt vmcnt(40)
	v_lshlrev_b32_e32 v110, 16, v46
	v_and_b32_e32 v111, 0xffff0000, v46
	v_lshlrev_b32_e32 v112, 16, v47
	v_and_b32_e32 v113, 0xffff0000, v47
	v_fma_f32 v0, v0, v91, v110
	v_fma_f32 v1, v1, v91, v111
	v_fma_f32 v2, v2, v91, v112
	v_fma_f32 v3, v3, v91, v113
	v_cvt_pk_bf16_f32 v106, v0, v1
	v_cvt_pk_bf16_f32 v107, v2, v3
	global_store_dwordx2 v[116:117], v[106:107], off
	v_lshl_add_u64 v[116:117], v[116:117], 0, s[12:13]
	s_waitcnt vmcnt(38)
	v_lshlrev_b32_e32 v110, 16, v48
	v_and_b32_e32 v111, 0xffff0000, v48
	v_lshlrev_b32_e32 v112, 16, v49
	v_and_b32_e32 v113, 0xffff0000, v49
	v_fma_f32 v0, v0, v92, v110
	v_fma_f32 v1, v1, v92, v111
	v_fma_f32 v2, v2, v92, v112
	v_fma_f32 v3, v3, v92, v113
	v_cvt_pk_bf16_f32 v108, v0, v1
	v_cvt_pk_bf16_f32 v109, v2, v3
	global_store_dwordx2 v[116:117], v[108:109], off
	v_lshl_add_u64 v[116:117], v[116:117], 0, s[12:13]
	s_waitcnt vmcnt(36)
	v_lshlrev_b32_e32 v110, 16, v50
	v_and_b32_e32 v111, 0xffff0000, v50
	v_lshlrev_b32_e32 v112, 16, v51
	v_and_b32_e32 v113, 0xffff0000, v51
	v_fma_f32 v0, v0, v93, v110
	v_fma_f32 v1, v1, v93, v111
	v_fma_f32 v2, v2, v93, v112
	v_fma_f32 v3, v3, v93, v113
	v_cvt_pk_bf16_f32 v106, v0, v1
	v_cvt_pk_bf16_f32 v107, v2, v3
	global_store_dwordx2 v[116:117], v[106:107], off
	v_lshl_add_u64 v[116:117], v[116:117], 0, s[12:13]
	s_waitcnt vmcnt(34)
; __device__ __forceinline__ unsigned pk2(float lo, float hi) { f32x2_t v = {lo, hi}; bf16x2_t b = __builtin_convertvector(v, bf16x2_t); return __builtin_bit_cast(unsigned, b); }
; __device__ __forceinline__ float bflo(unsigned u) { return __uint_as_float(u << 16); }
; __device__ __forceinline__ float bfhi(unsigned u) { return __uint_as_float(u & 0xffff0000u); }
; __device__ __forceinline__ void phase4_scan(const Params& p, int bid, int G) {
;     ...
; #pragma unroll 16
;         for (int c = 0; c < 32; ++c) {
;             const float dec = decay[(b * 32 + c) * 16 + h];
;             const size_t off = ((size_t)((b * 32 + c) * 16 + h) * 64 + pp) * 128 + n;
;             const uint2 su = *(const uint2*)(states + off);
;             const float4 st = make_float4(bflo(su.x), bfhi(su.x), bflo(su.y), bfhi(su.y));
;             uint2 o; o.x = pk2(hc.x, hc.y); o.y = pk2(hc.z, hc.w);
;             *(uint2*)(hprev + off) = o;
;             hc.x = hc.x * dec + st.x; hc.y = hc.y * dec + st.y; hc.z = hc.z * dec + st.z; hc.w = hc.w * dec + st.w;
;         }
;         *(float4*)(p.out + O_SP + ((size_t)(b * 16 + h) * 64 + pp) * 128 + n) = hc;
;     }
	v_lshlrev_b32_e32 v110, 16, v52
	v_and_b32_e32 v111, 0xffff0000, v52
	v_lshlrev_b32_e32 v112, 16, v53
	v_and_b32_e32 v113, 0xffff0000, v53
	v_fma_f32 v0, v0, v94, v110
	v_fma_f32 v1, v1, v94, v111
	v_fma_f32 v2, v2, v94, v112
	v_fma_f32 v3, v3, v94, v113
	v_cvt_pk_bf16_f32 v108, v0, v1
	v_cvt_pk_bf16_f32 v109, v2, v3
	global_store_dwordx2 v[116:117], v[108:109], off
	v_lshl_add_u64 v[116:117], v[116:117], 0, s[12:13]
	s_waitcnt vmcnt(32)
	v_lshlrev_b32_e32 v110, 16, v54
	v_and_b32_e32 v111, 0xffff0000, v54
	v_lshlrev_b32_e32 v112, 16, v55
	v_and_b32_e32 v113, 0xffff0000, v55
	v_fma_f32 v0, v0, v95, v110
	v_fma_f32 v1, v1, v95, v111
	v_fma_f32 v2, v2, v95, v112
	v_fma_f32 v3, v3, v95, v113
	v_cvt_pk_bf16_f32 v106, v0, v1
	v_cvt_pk_bf16_f32 v107, v2, v3
	global_store_dwordx2 v[116:117], v[106:107], off
	v_lshl_add_u64 v[116:117], v[116:117], 0, s[12:13]
	s_waitcnt vmcnt(30)
	v_lshlrev_b32_e32 v110, 16, v56
	v_and_b32_e32 v111, 0xffff0000, v56
	v_lshlrev_b32_e32 v112, 16, v57
	v_and_b32_e32 v113, 0xffff0000, v57
	v_fma_f32 v0, v0, v96, v110
	v_fma_f32 v1, v1, v96, v111
	v_fma_f32 v2, v2, v96, v112
	v_fma_f32 v3, v3, v96, v113
	v_cvt_pk_bf16_f32 v108, v0, v1
	v_cvt_pk_bf16_f32 v109, v2, v3
	global_store_dwordx2 v[116:117], v[108:109], off
	v_lshl_add_u64 v[116:117], v[116:117], 0, s[12:13]
	s_waitcnt vmcnt(28)
	v_lshlrev_b32_e32 v110, 16, v58
	v_and_b32_e32 v111, 0xffff0000, v58
	v_lshlrev_b32_e32 v112, 16, v59
	v_and_b32_e32 v113, 0xffff0000, v59
	v_fma_f32 v0, v0, v97, v110
	v_fma_f32 v1, v1, v97, v111
	v_fma_f32 v2, v2, v97, v112
	v_fma_f32 v3, v3, v97, v113
	v_cvt_pk_bf16_f32 v106, v0, v1
	v_cvt_pk_bf16_f32 v107, v2, v3
	global_store_dwordx2 v[116:117], v[106:107], off
	v_lshl_add_u64 v[116:117], v[116:117], 0, s[12:13]
	s_waitcnt vmcnt(26)
	v_lshlrev_b32_e32 v110, 16, v60
	v_and_b32_e32 v111, 0xffff0000, v60
	v_lshlrev_b32_e32 v112, 16, v61
	v_and_b32_e32 v113, 0xffff0000, v61
	v_fma_f32 v0, v0, v98, v110
	v_fma_f32 v1, v1, v98, v111
	v_fma_f32 v2, v2, v98, v112
	v_fma_f32 v3, v3, v98, v113
	v_cvt_pk_bf16_f32 v108, v0, v1
	v_cvt_pk_bf16_f32 v109, v2, v3
	global_store_dwordx2 v[116:117], v[108:109], off
	v_lshl_add_u64 v[116:117], v[116:117], 0, s[12:13]
	s_waitcnt vmcnt(24)
	v_lshlrev_b32_e32 v110, 16, v62
	v_and_b32_e32 v111, 0xffff0000, v62
	v_lshlrev_b32_e32 v112, 16, v63
	v_and_b32_e32 v113, 0xffff0000, v63
	v_fma_f32 v0, v0, v99, v110
	v_fma_f32 v1, v1, v99, v111
	v_fma_f32 v2, v2, v99, v112
	v_fma_f32 v3, v3, v99, v113
	v_cvt_pk_bf16_f32 v106, v0, v1
	v_cvt_pk_bf16_f32 v107, v2, v3
	global_store_dwordx2 v[116:117], v[106:107], off
	v_lshl_add_u64 v[116:117], v[116:117], 0, s[12:13]
	s_waitcnt vmcnt(22)
	v_lshlrev_b32_e32 v110, 16, v64
	v_and_b32_e32 v111, 0xffff0000, v64
	v_lshlrev_b32_e32 v112, 16, v65
	v_and_b32_e32 v113, 0xffff0000, v65
	v_fma_f32 v0, v0, v100, v110
	v_fma_f32 v1, v1, v100, v111
	v_fma_f32 v2, v2, v100, v112
	v_fma_f32 v3, v3, v100, v113
	v_cvt_pk_bf16_f32 v108, v0, v1
	v_cvt_pk_bf16_f32 v109, v2, v3
	global_store_dwordx2 v[116:117], v[108:109], off
	v_lshl_add_u64 v[116:117], v[116:117], 0, s[12:13]
	s_waitcnt vmcnt(20)
	v_lshlrev_b32_e32 v110, 16, v66
	v_and_b32_e32 v111, 0xffff0000, v66
	v_lshlrev_b32_e32 v112, 16, v67
	v_and_b32_e32 v113, 0xffff0000, v67
	v_fma_f32 v0, v0, v101, v110
	v_fma_f32 v1, v1, v101, v111
	v_fma_f32 v2, v2, v101, v112
	v_fma_f32 v3, v3, v101, v113
	v_cvt_pk_bf16_f32 v106, v0, v1
	v_cvt_pk_bf16_f32 v107, v2, v3
	global_store_dwordx2 v[116:117], v[106:107], off
	v_lshl_add_u64 v[116:117], v[116:117], 0, s[12:13]
	s_waitcnt vmcnt(18)
	v_lshlrev_b32_e32 v110, 16, v68
	v_and_b32_e32 v111, 0xffff0000, v68
	v_lshlrev_b32_e32 v112, 16, v69
	v_and_b32_e32 v113, 0xffff0000, v69
	v_fma_f32 v0, v0, v102, v110
	v_fma_f32 v1, v1, v102, v111
	v_fma_f32 v2, v2, v102, v112
	v_fma_f32 v3, v3, v102, v113
	v_cvt_pk_bf16_f32 v108, v0, v1
	v_cvt_pk_bf16_f32 v109, v2, v3
	global_store_dwordx2 v[116:117], v[108:109], off
	s_waitcnt vmcnt(16)
	v_lshlrev_b32_e32 v110, 16, v70
	v_and_b32_e32 v111, 0xffff0000, v70
	v_lshlrev_b32_e32 v112, 16, v71
	v_and_b32_e32 v113, 0xffff0000, v71
	v_fma_f32 v0, v0, v103, v110
	v_fma_f32 v1, v1, v103, v111
	v_fma_f32 v2, v2, v103, v112
	v_fma_f32 v3, v3, v103, v113
	v_ashrrev_i32_e32 v81, 15, v178
	v_and_b32_e32 v6, 15, v6
	v_lshl_or_b32 v8, v81, 4, v6
	v_ashrrev_i32_e32 v9, 31, v8
	v_lshlrev_b64 v[8:9], 15, v[8:9]
	v_lshlrev_b32_e32 v10, 4, v178
	v_lshl_add_u64 v[8:9], s[8:9], 0, v[8:9]
	v_and_b32_e32 v6, 0x7e00, v10
	v_add_u32_e32 v178, s40, v178
	v_lshl_add_u64 v[8:9], v[8:9], 0, v[6:7]
	v_and_b32_e32 v6, 0x1f0, v10
	v_cmp_lt_i32_e32 vcc, s18, v178
	v_lshl_add_u64 v[8:9], v[8:9], 0, v[6:7]
	s_or_b64 s[4:5], vcc, s[4:5]
	v_add_u32_e32 v80, s3, v80
	global_store_dwordx4 v[8:9], v[0:3], off
	s_andn2_b64 exec, exec, s[4:5]
	s_cbranch_execnz .LBB0_467
